# hand-scheduled attention full-tile path (ds_read ring + interleaved softmax) and 2x-unrolled phase 7
# speedup vs baseline: 1.0212x; 1.0212x over previous
.LBB0_628:
	s_or_b64 exec, exec, s[74:75]
	s_cmpk_lt_u32 s84, 0x400
	s_waitcnt vmcnt(0) lgkmcnt(0)
	s_barrier
	s_cbranch_scc0 .LBB0_659
	v_lshlrev_b32_e32 v2, 1, v174
	v_lshlrev_b32_e32 v234, 1, v176
	v_mov_b32_e32 v235, v3
	s_lshl_b32 s74, s78, 1
	v_lshl_add_u32 v183, s79, 2, v244
	s_lshl_b32 s96, s79, 1
	v_lshl_add_u64 v[228:229], v[4:5], 0, s[72:73]
	v_lshl_add_u64 v[230:231], v[6:7], 0, s[72:73]
	v_lshl_add_u64 v[232:233], v[8:9], 0, v[2:3]
	v_lshl_add_u64 v[236:237], v[10:11], 0, v[234:235]
	s_sub_i32 s97, 32, s74
	v_mov_b32_e32 v238, v3
	v_mov_b32_e32 v239, v3
	v_mov_b32_e32 v4, v3
	v_mov_b32_e32 v5, v3
	v_mov_b32_e32 v6, v3
	v_mov_b32_e32 v7, v3
	v_mov_b32_e32 v8, v3
	v_mov_b32_e32 v9, v3
	v_mov_b32_e32 v10, v3
	v_mov_b32_e32 v11, v3
	v_mov_b32_e32 v12, v3
	v_mov_b32_e32 v13, v3
	v_mov_b32_e32 v14, v3
	v_mov_b32_e32 v15, v3
	v_mov_b32_e32 v16, v3
	v_mov_b32_e32 v17, v3
	v_mov_b32_e32 v18, v3
	v_mov_b32_e32 v19, v3
	v_mov_b32_e32 v20, v3
	v_mov_b32_e32 v21, v3
	v_mov_b32_e32 v22, v3
	v_mov_b32_e32 v23, v3
	v_mov_b32_e32 v24, v3
	v_mov_b32_e32 v25, v3
	v_mov_b32_e32 v26, v3
	v_mov_b32_e32 v27, v3
	v_mov_b32_e32 v28, v3
	v_mov_b32_e32 v29, v3
	v_mov_b32_e32 v30, v3
	v_mov_b32_e32 v31, v3
	v_mov_b32_e32 v32, v3
	v_mov_b32_e32 v33, v3
	v_mov_b32_e32 v34, v3
	v_mov_b32_e32 v35, v3
	s_mov_b32 s90, 0
	s_mov_b32 s86, 0
	s_branch .LBB0_632
.LBB0_631:
	s_or_b64 exec, exec, s[74:75]
	s_add_i32 s86, s86, 1
	s_add_i32 s90, s90, 2
	s_cmp_eq_u32 s97, s86
	s_waitcnt vmcnt(0) lgkmcnt(0)
	s_barrier
	s_cbranch_scc1 .LBB0_589

.LBB0_646:
	s_andn2_saveexec_b64 s[74:75], s[74:75]
	s_cbranch_execz .LBB0_631
	v_mov_b32_e32 v124, v68
	ds_read_b128 v[100:103], v124
	ds_read_b128 v[104:107], v124 offset:32
	ds_read_b128 v[108:111], v124 offset:64
	ds_read_b128 v[112:115], v124 offset:96
	ds_read_b128 v[116:119], v124 offset:128
	ds_read_b128 v[120:123], v124 offset:160
	v_xor_b32_e32 v84, 0x80000000, v239
	v_mov_b32_e32 v85, v84
	v_mov_b32_e32 v86, v84
	v_mov_b32_e32 v87, v84
	v_mov_b32_e32 v88, v84
	v_mov_b32_e32 v89, v84
	v_mov_b32_e32 v90, v84
	v_mov_b32_e32 v91, v84
	v_mov_b32_e32 v92, v84
	v_mov_b32_e32 v93, v84
	v_mov_b32_e32 v94, v84
	v_mov_b32_e32 v95, v84
	v_mov_b32_e32 v96, v84
	v_mov_b32_e32 v97, v84
	v_mov_b32_e32 v98, v84
	v_mov_b32_e32 v99, v84
	s_waitcnt lgkmcnt(5)
	s_nop 0
	v_mfma_f32_32x32x16_bf16 v[36:51], v[100:103], v[132:135], v[84:99]
	ds_read_b128 v[100:103], v124 offset:6656
	s_waitcnt lgkmcnt(5)
	v_mfma_f32_32x32x16_bf16 v[36:51], v[104:107], v[136:139], v[36:51]
	ds_read_b128 v[104:107], v124 offset:6688
	s_waitcnt lgkmcnt(5)
	v_mfma_f32_32x32x16_bf16 v[36:51], v[108:111], v[140:143], v[36:51]
	ds_read_b128 v[108:111], v124 offset:6720
	s_waitcnt lgkmcnt(5)
	v_mfma_f32_32x32x16_bf16 v[36:51], v[112:115], v[144:147], v[36:51]
	ds_read_b128 v[112:115], v124 offset:6752
	s_waitcnt lgkmcnt(5)
	v_mfma_f32_32x32x16_bf16 v[36:51], v[116:119], v[148:151], v[36:51]
	ds_read_b128 v[116:119], v124 offset:6784
	s_waitcnt lgkmcnt(5)
	v_mfma_f32_32x32x16_bf16 v[36:51], v[120:123], v[152:155], v[36:51]
	ds_read_b128 v[120:123], v124 offset:6816
	s_waitcnt lgkmcnt(5)
	v_mfma_f32_32x32x16_bf16 v[52:67], v[100:103], v[132:135], v[84:99]
	ds_read_b128 v[100:103], v124 offset:13312
	s_waitcnt lgkmcnt(5)
	v_mfma_f32_32x32x16_bf16 v[52:67], v[104:107], v[136:139], v[52:67]
	ds_read_b128 v[104:107], v124 offset:13344
	s_waitcnt lgkmcnt(5)
	v_mfma_f32_32x32x16_bf16 v[52:67], v[108:111], v[140:143], v[52:67]
	ds_read_b128 v[108:111], v124 offset:13376
	s_waitcnt lgkmcnt(5)
	v_mfma_f32_32x32x16_bf16 v[52:67], v[112:115], v[144:147], v[52:67]
	ds_read_b128 v[112:115], v124 offset:13408
	s_waitcnt lgkmcnt(5)
	v_mfma_f32_32x32x16_bf16 v[52:67], v[116:119], v[148:151], v[52:67]
	ds_read_b128 v[116:119], v124 offset:13440
	s_waitcnt lgkmcnt(5)
	v_mfma_f32_32x32x16_bf16 v[52:67], v[120:123], v[152:155], v[52:67]
	ds_read_b128 v[120:123], v124 offset:13472
	s_waitcnt lgkmcnt(5)
	v_mfma_f32_32x32x16_bf16 v[68:83], v[100:103], v[132:135], v[84:99]
	ds_read_b128 v[100:103], v124 offset:19968
	v_max3_f32 v125, v36, v37, v38
	v_max3_f32 v125, v125, v39, v40
	v_max3_f32 v125, v125, v41, v42
	v_max3_f32 v125, v125, v43, v44
	s_waitcnt lgkmcnt(5)
	v_mfma_f32_32x32x16_bf16 v[68:83], v[104:107], v[136:139], v[68:83]
	ds_read_b128 v[104:107], v124 offset:20000
	v_max3_f32 v125, v125, v45, v46
	v_max3_f32 v125, v125, v47, v48
	v_max3_f32 v125, v125, v49, v50
	v_max3_f32 v129, v51, v52, v53
	s_waitcnt lgkmcnt(5)
	v_mfma_f32_32x32x16_bf16 v[68:83], v[108:111], v[140:143], v[68:83]
	ds_read_b128 v[108:111], v124 offset:20032
	v_max3_f32 v129, v129, v54, v55
	v_max3_f32 v129, v129, v56, v57
	v_max3_f32 v129, v129, v58, v59
	v_max3_f32 v129, v129, v60, v61
	s_waitcnt lgkmcnt(5)
	v_mfma_f32_32x32x16_bf16 v[68:83], v[112:115], v[144:147], v[68:83]
	ds_read_b128 v[112:115], v124 offset:20064
	v_max3_f32 v129, v129, v62, v63
	v_max3_f32 v129, v129, v64, v65
	v_max3_f32 v129, v129, v66, v67
	v_max_f32_e32 v125, v125, v129
	s_waitcnt lgkmcnt(5)
	v_mfma_f32_32x32x16_bf16 v[68:83], v[116:119], v[148:151], v[68:83]
	ds_read_b128 v[116:119], v124 offset:20096
	v_mov_b32_e32 v126, v125
	s_nop 1
	v_permlane32_swap_b32_e32 v125, v126
	v_max_f32_e32 v125, v125, v126
	s_cmp_eq_u32 s86, 0
	s_cbranch_scc1 .Latt_slow0
	v_cmp_lt_f32_e32 vcc, s95, v125
	s_cbranch_vccnz .Latt_slow0
	s_waitcnt lgkmcnt(5)
	v_mfma_f32_32x32x16_bf16 v[68:83], v[120:123], v[152:155], v[68:83]
	ds_read_b128 v[120:123], v124 offset:20128
	v_exp_f32_e32 v36, v36
	v_exp_f32_e32 v37, v37
	v_exp_f32_e32 v38, v38
	v_exp_f32_e32 v39, v39
	v_exp_f32_e32 v40, v40
	v_exp_f32_e32 v41, v41
	v_exp_f32_e32 v42, v42
	v_exp_f32_e32 v43, v43
	v_add_f32_e32 v127, v36, v37
	v_add_f32_e32 v127, v38, v127
	v_add_f32_e32 v127, v39, v127
	v_add_f32_e32 v127, v40, v127
	s_waitcnt lgkmcnt(5)
	v_mfma_f32_32x32x16_bf16 v[84:99], v[100:103], v[132:135], v[84:99]
	ds_read_b128 v[100:103], v185 offset:26624
	v_add_f32_e32 v127, v41, v127
	v_add_f32_e32 v127, v42, v127
	v_add_f32_e32 v127, v43, v127
	v_cvt_pk_bf16_f32 v36, v36, v37
	v_cvt_pk_bf16_f32 v37, v38, v39
	v_cvt_pk_bf16_f32 v38, v40, v41
	v_cvt_pk_bf16_f32 v39, v42, v43
	v_exp_f32_e32 v44, v44
	v_exp_f32_e32 v45, v45
	v_exp_f32_e32 v46, v46
	v_exp_f32_e32 v47, v47
	v_exp_f32_e32 v48, v48
	s_waitcnt lgkmcnt(5)
	v_mfma_f32_32x32x16_bf16 v[84:99], v[104:107], v[136:139], v[84:99]
	ds_read_b128 v[104:107], v185 offset:35328
	v_exp_f32_e32 v49, v49
	v_exp_f32_e32 v50, v50
	v_exp_f32_e32 v51, v51
	v_add_f32_e32 v127, v44, v127
	v_add_f32_e32 v127, v45, v127
	v_add_f32_e32 v127, v46, v127
	v_add_f32_e32 v127, v47, v127
	v_add_f32_e32 v127, v48, v127
	v_add_f32_e32 v127, v49, v127
	v_add_f32_e32 v127, v50, v127
	v_add_f32_e32 v127, v51, v127
	v_cvt_pk_bf16_f32 v40, v44, v45
	s_waitcnt lgkmcnt(5)
	v_mfma_f32_32x32x16_bf16 v[84:99], v[108:111], v[140:143], v[84:99]
	ds_read_b128 v[108:111], v185 offset:26656
	v_cvt_pk_bf16_f32 v41, v46, v47
	v_cvt_pk_bf16_f32 v42, v48, v49
	v_cvt_pk_bf16_f32 v43, v50, v51
	v_exp_f32_e32 v52, v52
	v_exp_f32_e32 v53, v53
	v_exp_f32_e32 v54, v54
	v_exp_f32_e32 v55, v55
	v_exp_f32_e32 v56, v56
	v_exp_f32_e32 v57, v57
	v_exp_f32_e32 v58, v58
	v_exp_f32_e32 v59, v59
	v_add_f32_e32 v128, v52, v53
	s_waitcnt lgkmcnt(5)
	v_mfma_f32_32x32x16_bf16 v[84:99], v[112:115], v[144:147], v[84:99]
	ds_read_b128 v[112:115], v185 offset:35360
	v_add_f32_e32 v128, v54, v128
	v_add_f32_e32 v128, v55, v128
	v_add_f32_e32 v128, v56, v128
	v_add_f32_e32 v128, v57, v128
	v_add_f32_e32 v128, v58, v128
	v_add_f32_e32 v128, v59, v128
	v_cvt_pk_bf16_f32 v52, v52, v53
	v_cvt_pk_bf16_f32 v53, v54, v55
	v_cvt_pk_bf16_f32 v54, v56, v57
	v_cvt_pk_bf16_f32 v55, v58, v59
	v_exp_f32_e32 v60, v60
	v_exp_f32_e32 v61, v61
	s_waitcnt lgkmcnt(5)
	v_mfma_f32_32x32x16_bf16 v[84:99], v[116:119], v[148:151], v[84:99]
	ds_read_b128 v[116:119], v185 offset:26688
	v_exp_f32_e32 v62, v62
	v_exp_f32_e32 v63, v63
	v_exp_f32_e32 v64, v64
	v_exp_f32_e32 v65, v65
	v_exp_f32_e32 v66, v66
	v_exp_f32_e32 v67, v67
	v_add_f32_e32 v128, v60, v128
	v_add_f32_e32 v128, v61, v128
	v_add_f32_e32 v128, v62, v128
	v_add_f32_e32 v128, v63, v128
	v_add_f32_e32 v128, v64, v128
	v_add_f32_e32 v128, v65, v128
	s_waitcnt lgkmcnt(5)
	v_mfma_f32_32x32x16_bf16 v[84:99], v[120:123], v[152:155], v[84:99]
	ds_read_b128 v[120:123], v185 offset:35392
	v_add_f32_e32 v128, v66, v128
	v_add_f32_e32 v128, v67, v128
	v_cvt_pk_bf16_f32 v56, v60, v61
	v_cvt_pk_bf16_f32 v57, v62, v63
	v_cvt_pk_bf16_f32 v58, v64, v65
	v_cvt_pk_bf16_f32 v59, v66, v67
	v_add_f32_e32 v127, v127, v128
	v_add_f32_e32 v238, v238, v127
	s_waitcnt lgkmcnt(5)
	v_mfma_f32_32x32x16_bf16 v[4:19], v[100:103], v[36:39], v[4:19]
	ds_read_b128 v[100:103], v185 offset:26720
	v_max3_f32 v125, v68, v69, v70
	v_max3_f32 v125, v125, v71, v72
	v_max3_f32 v125, v125, v73, v74
	v_max3_f32 v125, v125, v75, v76
	v_max3_f32 v125, v125, v77, v78
	v_max3_f32 v125, v125, v79, v80
	v_max3_f32 v125, v125, v81, v82
	s_waitcnt lgkmcnt(5)
	v_mfma_f32_32x32x16_bf16 v[20:35], v[104:107], v[36:39], v[20:35]
	ds_read_b128 v[104:107], v185 offset:35424
	v_max3_f32 v129, v83, v84, v85
	v_max3_f32 v129, v129, v86, v87
	v_max3_f32 v129, v129, v88, v89
	v_max3_f32 v129, v129, v90, v91
	v_max3_f32 v129, v129, v92, v93
	v_max3_f32 v129, v129, v94, v95
	v_max3_f32 v129, v129, v96, v97
	s_waitcnt lgkmcnt(5)
	v_mfma_f32_32x32x16_bf16 v[4:19], v[108:111], v[40:43], v[4:19]
	ds_read_b128 v[108:111], v185 offset:26752
	v_max3_f32 v129, v129, v98, v99
	v_max_f32_e32 v125, v125, v129
	v_mov_b32_e32 v126, v125
	s_nop 1
	v_permlane32_swap_b32_e32 v125, v126
	v_max_f32_e32 v125, v125, v126
	v_cmp_lt_f32_e32 vcc, s95, v125
	s_cbranch_vccnz .Latt_slow1
	s_waitcnt lgkmcnt(5)
	v_mfma_f32_32x32x16_bf16 v[20:35], v[112:115], v[40:43], v[20:35]
	ds_read_b128 v[112:115], v185 offset:35456
	v_exp_f32_e32 v68, v68
	v_exp_f32_e32 v69, v69
	v_exp_f32_e32 v70, v70
	v_exp_f32_e32 v71, v71
	v_exp_f32_e32 v72, v72
	v_exp_f32_e32 v73, v73
	v_exp_f32_e32 v74, v74
	v_exp_f32_e32 v75, v75
	v_add_f32_e32 v127, v68, v69
	v_add_f32_e32 v127, v70, v127
	v_add_f32_e32 v127, v71, v127
	v_add_f32_e32 v127, v72, v127
	v_add_f32_e32 v127, v73, v127
	v_add_f32_e32 v127, v74, v127
	v_add_f32_e32 v127, v75, v127
	v_cvt_pk_bf16_f32 v68, v68, v69
	s_waitcnt lgkmcnt(5)
	v_mfma_f32_32x32x16_bf16 v[4:19], v[116:119], v[52:55], v[4:19]
	ds_read_b128 v[116:119], v185 offset:26784
	v_cvt_pk_bf16_f32 v69, v70, v71
	v_cvt_pk_bf16_f32 v70, v72, v73
	v_cvt_pk_bf16_f32 v71, v74, v75
	v_exp_f32_e32 v76, v76
	v_exp_f32_e32 v77, v77
	v_exp_f32_e32 v78, v78
	v_exp_f32_e32 v79, v79
	v_exp_f32_e32 v80, v80
	v_exp_f32_e32 v81, v81
	v_exp_f32_e32 v82, v82
	v_exp_f32_e32 v83, v83
	v_add_f32_e32 v127, v76, v127
	v_add_f32_e32 v127, v77, v127
	v_add_f32_e32 v127, v78, v127
	v_add_f32_e32 v127, v79, v127
	v_add_f32_e32 v127, v80, v127
	s_waitcnt lgkmcnt(5)
	v_mfma_f32_32x32x16_bf16 v[20:35], v[120:123], v[52:55], v[20:35]
	ds_read_b128 v[120:123], v185 offset:35488
	v_add_f32_e32 v127, v81, v127
	v_add_f32_e32 v127, v82, v127
	v_add_f32_e32 v127, v83, v127
	v_cvt_pk_bf16_f32 v72, v76, v77
	v_cvt_pk_bf16_f32 v73, v78, v79
	v_cvt_pk_bf16_f32 v74, v80, v81
	v_cvt_pk_bf16_f32 v75, v82, v83
	v_exp_f32_e32 v84, v84
	v_exp_f32_e32 v85, v85
	v_exp_f32_e32 v86, v86
	v_exp_f32_e32 v87, v87
	v_exp_f32_e32 v88, v88
	v_exp_f32_e32 v89, v89
	v_exp_f32_e32 v90, v90
	v_exp_f32_e32 v91, v91
	v_add_f32_e32 v128, v84, v85
	s_waitcnt lgkmcnt(5)
	v_mfma_f32_32x32x16_bf16 v[4:19], v[100:103], v[56:59], v[4:19]
	ds_read_b128 v[100:103], v185 offset:26816
	v_add_f32_e32 v128, v86, v128
	v_add_f32_e32 v128, v87, v128
	v_add_f32_e32 v128, v88, v128
	v_add_f32_e32 v128, v89, v128
	v_add_f32_e32 v128, v90, v128
	v_add_f32_e32 v128, v91, v128
	v_cvt_pk_bf16_f32 v84, v84, v85
	v_cvt_pk_bf16_f32 v85, v86, v87
	v_cvt_pk_bf16_f32 v86, v88, v89
	v_cvt_pk_bf16_f32 v87, v90, v91
	v_exp_f32_e32 v92, v92
	v_exp_f32_e32 v93, v93
	v_exp_f32_e32 v94, v94
	v_exp_f32_e32 v95, v95
	v_exp_f32_e32 v96, v96
	v_exp_f32_e32 v97, v97
	s_waitcnt lgkmcnt(5)
	v_mfma_f32_32x32x16_bf16 v[20:35], v[104:107], v[56:59], v[20:35]
	ds_read_b128 v[104:107], v185 offset:35520
	v_exp_f32_e32 v98, v98
	v_exp_f32_e32 v99, v99
	v_add_f32_e32 v128, v92, v128
	v_add_f32_e32 v128, v93, v128
	v_add_f32_e32 v128, v94, v128
	v_add_f32_e32 v128, v95, v128
	v_add_f32_e32 v128, v96, v128
	v_add_f32_e32 v128, v97, v128
	v_add_f32_e32 v128, v98, v128
	v_add_f32_e32 v128, v99, v128
	v_cvt_pk_bf16_f32 v88, v92, v93
	v_cvt_pk_bf16_f32 v89, v94, v95
	v_cvt_pk_bf16_f32 v90, v96, v97
	v_cvt_pk_bf16_f32 v91, v98, v99
	v_add_f32_e32 v127, v127, v128
	v_add_f32_e32 v238, v238, v127
	s_waitcnt lgkmcnt(5)
	v_mfma_f32_32x32x16_bf16 v[4:19], v[108:111], v[68:71], v[4:19]
	ds_read_b128 v[108:111], v185 offset:26848
	s_waitcnt lgkmcnt(5)
	v_mfma_f32_32x32x16_bf16 v[20:35], v[112:115], v[68:71], v[20:35]
	ds_read_b128 v[112:115], v185 offset:35552
	s_waitcnt lgkmcnt(5)
	v_mfma_f32_32x32x16_bf16 v[4:19], v[116:119], v[72:75], v[4:19]
	s_waitcnt lgkmcnt(4)
	v_mfma_f32_32x32x16_bf16 v[20:35], v[120:123], v[72:75], v[20:35]
	s_waitcnt lgkmcnt(3)
	v_mfma_f32_32x32x16_bf16 v[4:19], v[100:103], v[84:87], v[4:19]
	s_waitcnt lgkmcnt(2)
	v_mfma_f32_32x32x16_bf16 v[20:35], v[104:107], v[84:87], v[20:35]
	s_waitcnt lgkmcnt(1)
	v_mfma_f32_32x32x16_bf16 v[4:19], v[108:111], v[88:91], v[4:19]
	s_waitcnt lgkmcnt(0)
	v_mfma_f32_32x32x16_bf16 v[20:35], v[112:115], v[88:91], v[20:35]
	s_branch .LBB0_631
.Latt_slow0:
	s_waitcnt lgkmcnt(5)
	v_mfma_f32_32x32x16_bf16 v[68:83], v[120:123], v[152:155], v[68:83]
	ds_read_b128 v[120:123], v124 offset:20128
	s_waitcnt lgkmcnt(5)
	v_mfma_f32_32x32x16_bf16 v[84:99], v[100:103], v[132:135], v[84:99]
	ds_read_b128 v[100:103], v185 offset:26624
	s_waitcnt lgkmcnt(5)
	v_mfma_f32_32x32x16_bf16 v[84:99], v[104:107], v[136:139], v[84:99]
	ds_read_b128 v[104:107], v185 offset:35328
	s_waitcnt lgkmcnt(5)
	v_mfma_f32_32x32x16_bf16 v[84:99], v[108:111], v[140:143], v[84:99]
	ds_read_b128 v[108:111], v185 offset:26656
	s_waitcnt lgkmcnt(5)
	v_mfma_f32_32x32x16_bf16 v[84:99], v[112:115], v[144:147], v[84:99]
	ds_read_b128 v[112:115], v185 offset:35360
	s_waitcnt lgkmcnt(5)
	v_mfma_f32_32x32x16_bf16 v[84:99], v[116:119], v[148:151], v[84:99]
	ds_read_b128 v[116:119], v185 offset:26688
	s_waitcnt lgkmcnt(5)
	v_mfma_f32_32x32x16_bf16 v[84:99], v[120:123], v[152:155], v[84:99]
	ds_read_b128 v[120:123], v185 offset:35392
	v_max_f32_e32 v130, 0, v125
	s_cmp_eq_u32 s86, 0
	s_cselect_b64 s[78:79], -1, 0
	v_cndmask_b32_e64 v130, v130, v125, s[78:79]
	v_exp_f32_e64 v131, -v130
	v_mov_b32_e32 v187, v130
	v_add_f32_e32 v239, v239, v130
	v_cndmask_b32_e64 v131, v131, 0, s[78:79]
	v_sub_f32_e32 v36, v36, v187
	v_sub_f32_e32 v37, v37, v187
	v_sub_f32_e32 v38, v38, v187
	v_sub_f32_e32 v39, v39, v187
	v_sub_f32_e32 v40, v40, v187
	v_sub_f32_e32 v41, v41, v187
	v_sub_f32_e32 v42, v42, v187
	v_sub_f32_e32 v43, v43, v187
	v_sub_f32_e32 v44, v44, v187
	v_sub_f32_e32 v45, v45, v187
	v_sub_f32_e32 v46, v46, v187
	v_sub_f32_e32 v47, v47, v187
	v_sub_f32_e32 v48, v48, v187
	v_sub_f32_e32 v49, v49, v187
	v_sub_f32_e32 v50, v50, v187
	v_sub_f32_e32 v51, v51, v187
	v_sub_f32_e32 v52, v52, v187
	v_sub_f32_e32 v53, v53, v187
	v_sub_f32_e32 v54, v54, v187
	v_sub_f32_e32 v55, v55, v187
	v_sub_f32_e32 v56, v56, v187
	v_sub_f32_e32 v57, v57, v187
	v_sub_f32_e32 v58, v58, v187
	v_sub_f32_e32 v59, v59, v187
	v_sub_f32_e32 v60, v60, v187
	v_sub_f32_e32 v61, v61, v187
	v_sub_f32_e32 v62, v62, v187
	v_sub_f32_e32 v63, v63, v187
	v_sub_f32_e32 v64, v64, v187
	v_sub_f32_e32 v65, v65, v187
	v_sub_f32_e32 v66, v66, v187
	v_sub_f32_e32 v67, v67, v187
	v_exp_f32_e32 v36, v36
	v_exp_f32_e32 v37, v37
	v_exp_f32_e32 v38, v38
	v_exp_f32_e32 v39, v39
	v_exp_f32_e32 v40, v40
	v_exp_f32_e32 v41, v41
	v_exp_f32_e32 v42, v42
	v_exp_f32_e32 v43, v43
	v_exp_f32_e32 v44, v44
	v_exp_f32_e32 v45, v45
	v_exp_f32_e32 v46, v46
	v_exp_f32_e32 v47, v47
	v_exp_f32_e32 v48, v48
	v_exp_f32_e32 v49, v49
	v_exp_f32_e32 v50, v50
	v_exp_f32_e32 v51, v51
	v_exp_f32_e32 v52, v52
	v_exp_f32_e32 v53, v53
	v_exp_f32_e32 v54, v54
	v_exp_f32_e32 v55, v55
	v_exp_f32_e32 v56, v56
	v_exp_f32_e32 v57, v57
	v_exp_f32_e32 v58, v58
	v_exp_f32_e32 v59, v59
	v_exp_f32_e32 v60, v60
	v_exp_f32_e32 v61, v61
	v_exp_f32_e32 v62, v62
	v_exp_f32_e32 v63, v63
	v_exp_f32_e32 v64, v64
	v_exp_f32_e32 v65, v65
	v_exp_f32_e32 v66, v66
	v_exp_f32_e32 v67, v67
	v_add_f32_e32 v127, v36, v37
	v_add_f32_e32 v127, v38, v127
	v_add_f32_e32 v127, v39, v127
	v_add_f32_e32 v127, v40, v127
	v_add_f32_e32 v127, v41, v127
	v_add_f32_e32 v127, v42, v127
	v_add_f32_e32 v127, v43, v127
	v_add_f32_e32 v127, v44, v127
	v_add_f32_e32 v127, v45, v127
	v_add_f32_e32 v127, v46, v127
	v_add_f32_e32 v127, v47, v127
	v_add_f32_e32 v127, v48, v127
	v_add_f32_e32 v127, v49, v127
	v_add_f32_e32 v127, v50, v127
	v_add_f32_e32 v127, v51, v127
	v_add_f32_e32 v127, v52, v127
	v_add_f32_e32 v127, v53, v127
	v_add_f32_e32 v127, v54, v127
	v_add_f32_e32 v127, v55, v127
	v_add_f32_e32 v127, v56, v127
	v_add_f32_e32 v127, v57, v127
	v_add_f32_e32 v127, v58, v127
	v_add_f32_e32 v127, v59, v127
	v_add_f32_e32 v127, v60, v127
	v_add_f32_e32 v127, v61, v127
	v_add_f32_e32 v127, v62, v127
	v_add_f32_e32 v127, v63, v127
	v_add_f32_e32 v127, v64, v127
	v_add_f32_e32 v127, v65, v127
	v_add_f32_e32 v127, v66, v127
	v_add_f32_e32 v127, v67, v127
	v_mul_f32_e32 v238, v238, v131
	v_add_f32_e32 v238, v238, v127
	v_mul_f32_e32 v4, v4, v131
	v_mul_f32_e32 v5, v5, v131
	v_mul_f32_e32 v6, v6, v131
	v_mul_f32_e32 v7, v7, v131
	v_mul_f32_e32 v8, v8, v131
	v_mul_f32_e32 v9, v9, v131
	v_mul_f32_e32 v10, v10, v131
	v_mul_f32_e32 v11, v11, v131
	v_mul_f32_e32 v12, v12, v131
	v_mul_f32_e32 v13, v13, v131
	v_mul_f32_e32 v14, v14, v131
	v_mul_f32_e32 v15, v15, v131
	v_mul_f32_e32 v16, v16, v131
	v_mul_f32_e32 v17, v17, v131
	v_mul_f32_e32 v18, v18, v131
	v_mul_f32_e32 v19, v19, v131
	v_mul_f32_e32 v20, v20, v131
	v_mul_f32_e32 v21, v21, v131
	v_mul_f32_e32 v22, v22, v131
	v_mul_f32_e32 v23, v23, v131
	v_mul_f32_e32 v24, v24, v131
	v_mul_f32_e32 v25, v25, v131
	v_mul_f32_e32 v26, v26, v131
	v_mul_f32_e32 v27, v27, v131
	v_mul_f32_e32 v28, v28, v131
	v_mul_f32_e32 v29, v29, v131
	v_mul_f32_e32 v30, v30, v131
	v_mul_f32_e32 v31, v31, v131
	v_mul_f32_e32 v32, v32, v131
	v_mul_f32_e32 v33, v33, v131
	v_mul_f32_e32 v34, v34, v131
	v_mul_f32_e32 v35, v35, v131
	v_mov_b32_e32 v242, v130
	v_cvt_pk_bf16_f32 v36, v36, v37
	v_cvt_pk_bf16_f32 v37, v38, v39
	v_cvt_pk_bf16_f32 v38, v40, v41
	v_cvt_pk_bf16_f32 v39, v42, v43
	v_cvt_pk_bf16_f32 v40, v44, v45
	v_cvt_pk_bf16_f32 v41, v46, v47
	v_cvt_pk_bf16_f32 v42, v48, v49
	v_cvt_pk_bf16_f32 v43, v50, v51
	v_cvt_pk_bf16_f32 v52, v52, v53
	v_cvt_pk_bf16_f32 v53, v54, v55
	v_cvt_pk_bf16_f32 v54, v56, v57
	v_cvt_pk_bf16_f32 v55, v58, v59
	v_cvt_pk_bf16_f32 v56, v60, v61
	v_cvt_pk_bf16_f32 v57, v62, v63
	v_cvt_pk_bf16_f32 v58, v64, v65
	v_cvt_pk_bf16_f32 v59, v66, v67
	s_waitcnt lgkmcnt(5)
	v_mfma_f32_32x32x16_bf16 v[4:19], v[100:103], v[36:39], v[4:19]
	ds_read_b128 v[100:103], v185 offset:26720
	s_waitcnt lgkmcnt(5)
	v_mfma_f32_32x32x16_bf16 v[20:35], v[104:107], v[36:39], v[20:35]
	ds_read_b128 v[104:107], v185 offset:35424
	s_waitcnt lgkmcnt(5)
	v_mfma_f32_32x32x16_bf16 v[4:19], v[108:111], v[40:43], v[4:19]
	ds_read_b128 v[108:111], v185 offset:26752
	s_branch .Latt_slowb

.Latt_slowb:
	s_waitcnt lgkmcnt(5)
	v_mfma_f32_32x32x16_bf16 v[20:35], v[112:115], v[40:43], v[20:35]
	ds_read_b128 v[112:115], v185 offset:35456
	s_waitcnt lgkmcnt(5)
	v_mfma_f32_32x32x16_bf16 v[4:19], v[116:119], v[52:55], v[4:19]
	ds_read_b128 v[116:119], v185 offset:26784
	s_waitcnt lgkmcnt(5)
	v_mfma_f32_32x32x16_bf16 v[20:35], v[120:123], v[52:55], v[20:35]
	ds_read_b128 v[120:123], v185 offset:35488
	s_waitcnt lgkmcnt(5)
	v_mfma_f32_32x32x16_bf16 v[4:19], v[100:103], v[56:59], v[4:19]
	ds_read_b128 v[100:103], v185 offset:26816
	s_waitcnt lgkmcnt(5)
	v_mfma_f32_32x32x16_bf16 v[20:35], v[104:107], v[56:59], v[20:35]
	ds_read_b128 v[104:107], v185 offset:35520
	v_max3_f32 v125, v68, v69, v70
	v_max3_f32 v125, v125, v71, v72
	v_max3_f32 v125, v125, v73, v74
	v_max3_f32 v125, v125, v75, v76
	v_max3_f32 v125, v125, v77, v78
	v_max3_f32 v125, v125, v79, v80
	v_max3_f32 v125, v125, v81, v82
	v_max3_f32 v129, v83, v84, v85
	v_max3_f32 v129, v129, v86, v87
	v_max3_f32 v129, v129, v88, v89
	v_max3_f32 v129, v129, v90, v91
	v_max3_f32 v129, v129, v92, v93
	v_max3_f32 v129, v129, v94, v95
	v_max3_f32 v129, v129, v96, v97
	v_max3_f32 v129, v129, v98, v99
	v_max_f32_e32 v125, v125, v129
	v_mov_b32_e32 v126, v125
	s_nop 1
	v_permlane32_swap_b32_e32 v125, v126
	v_max_f32_e32 v125, v125, v126
	v_sub_f32_e32 v125, v125, v242
	v_max_f32_e32 v130, 0, v125
	v_exp_f32_e64 v131, -v130
	v_add_f32_e32 v187, v242, v130
	v_add_f32_e32 v239, v239, v130
	v_sub_f32_e32 v68, v68, v187
	v_sub_f32_e32 v69, v69, v187
	v_sub_f32_e32 v70, v70, v187
	v_sub_f32_e32 v71, v71, v187
	v_sub_f32_e32 v72, v72, v187
	v_sub_f32_e32 v73, v73, v187
	v_sub_f32_e32 v74, v74, v187
	v_sub_f32_e32 v75, v75, v187
	v_sub_f32_e32 v76, v76, v187
	v_sub_f32_e32 v77, v77, v187
	v_sub_f32_e32 v78, v78, v187
	v_sub_f32_e32 v79, v79, v187
	v_sub_f32_e32 v80, v80, v187
	v_sub_f32_e32 v81, v81, v187
	v_sub_f32_e32 v82, v82, v187
	v_sub_f32_e32 v83, v83, v187
	v_sub_f32_e32 v84, v84, v187
	v_sub_f32_e32 v85, v85, v187
	v_sub_f32_e32 v86, v86, v187
	v_sub_f32_e32 v87, v87, v187
	v_sub_f32_e32 v88, v88, v187
	v_sub_f32_e32 v89, v89, v187
	v_sub_f32_e32 v90, v90, v187
	v_sub_f32_e32 v91, v91, v187
	v_sub_f32_e32 v92, v92, v187
	v_sub_f32_e32 v93, v93, v187
	v_sub_f32_e32 v94, v94, v187
	v_sub_f32_e32 v95, v95, v187
	v_sub_f32_e32 v96, v96, v187
	v_sub_f32_e32 v97, v97, v187
	v_sub_f32_e32 v98, v98, v187
	v_sub_f32_e32 v99, v99, v187
	v_exp_f32_e32 v68, v68
	v_exp_f32_e32 v69, v69
	v_exp_f32_e32 v70, v70
	v_exp_f32_e32 v71, v71
	v_exp_f32_e32 v72, v72
	v_exp_f32_e32 v73, v73
	v_exp_f32_e32 v74, v74
	v_exp_f32_e32 v75, v75
	v_exp_f32_e32 v76, v76
	v_exp_f32_e32 v77, v77
	v_exp_f32_e32 v78, v78
	v_exp_f32_e32 v79, v79
	v_exp_f32_e32 v80, v80
	v_exp_f32_e32 v81, v81
	v_exp_f32_e32 v82, v82
	v_exp_f32_e32 v83, v83
	v_exp_f32_e32 v84, v84
	v_exp_f32_e32 v85, v85
	v_exp_f32_e32 v86, v86
	v_exp_f32_e32 v87, v87
	v_exp_f32_e32 v88, v88
	v_exp_f32_e32 v89, v89
	v_exp_f32_e32 v90, v90
	v_exp_f32_e32 v91, v91
	v_exp_f32_e32 v92, v92
	v_exp_f32_e32 v93, v93
	v_exp_f32_e32 v94, v94
	v_exp_f32_e32 v95, v95
	v_exp_f32_e32 v96, v96
	v_exp_f32_e32 v97, v97
	v_exp_f32_e32 v98, v98
	v_exp_f32_e32 v99, v99
	v_add_f32_e32 v127, v68, v69
	v_add_f32_e32 v127, v70, v127
	v_add_f32_e32 v127, v71, v127
	v_add_f32_e32 v127, v72, v127
	v_add_f32_e32 v127, v73, v127
	v_add_f32_e32 v127, v74, v127
	v_add_f32_e32 v127, v75, v127
	v_add_f32_e32 v127, v76, v127
	v_add_f32_e32 v127, v77, v127
	v_add_f32_e32 v127, v78, v127
	v_add_f32_e32 v127, v79, v127
	v_add_f32_e32 v127, v80, v127
	v_add_f32_e32 v127, v81, v127
	v_add_f32_e32 v127, v82, v127
	v_add_f32_e32 v127, v83, v127
	v_add_f32_e32 v127, v84, v127
	v_add_f32_e32 v127, v85, v127
	v_add_f32_e32 v127, v86, v127
	v_add_f32_e32 v127, v87, v127
	v_add_f32_e32 v127, v88, v127
	v_add_f32_e32 v127, v89, v127
	v_add_f32_e32 v127, v90, v127
	v_add_f32_e32 v127, v91, v127
	v_add_f32_e32 v127, v92, v127
	v_add_f32_e32 v127, v93, v127
	v_add_f32_e32 v127, v94, v127
	v_add_f32_e32 v127, v95, v127
	v_add_f32_e32 v127, v96, v127
	v_add_f32_e32 v127, v97, v127
	v_add_f32_e32 v127, v98, v127
	v_add_f32_e32 v127, v99, v127
	v_mul_f32_e32 v238, v238, v131
	v_add_f32_e32 v238, v238, v127
	v_mul_f32_e32 v4, v4, v131
	v_mul_f32_e32 v5, v5, v131
	v_mul_f32_e32 v6, v6, v131
	v_mul_f32_e32 v7, v7, v131
	v_mul_f32_e32 v8, v8, v131
	v_mul_f32_e32 v9, v9, v131
	v_mul_f32_e32 v10, v10, v131
	v_mul_f32_e32 v11, v11, v131
	v_mul_f32_e32 v12, v12, v131
	v_mul_f32_e32 v13, v13, v131
	v_mul_f32_e32 v14, v14, v131
	v_mul_f32_e32 v15, v15, v131
	v_mul_f32_e32 v16, v16, v131
	v_mul_f32_e32 v17, v17, v131
	v_mul_f32_e32 v18, v18, v131
	v_mul_f32_e32 v19, v19, v131
	v_mul_f32_e32 v20, v20, v131
	v_mul_f32_e32 v21, v21, v131
	v_mul_f32_e32 v22, v22, v131
	v_mul_f32_e32 v23, v23, v131
	v_mul_f32_e32 v24, v24, v131
	v_mul_f32_e32 v25, v25, v131
	v_mul_f32_e32 v26, v26, v131
	v_mul_f32_e32 v27, v27, v131
	v_mul_f32_e32 v28, v28, v131
	v_mul_f32_e32 v29, v29, v131
	v_mul_f32_e32 v30, v30, v131
	v_mul_f32_e32 v31, v31, v131
	v_mul_f32_e32 v32, v32, v131
	v_mul_f32_e32 v33, v33, v131
	v_mul_f32_e32 v34, v34, v131
	v_mul_f32_e32 v35, v35, v131
	v_mov_b32_e32 v242, v130
	v_cvt_pk_bf16_f32 v68, v68, v69
	v_cvt_pk_bf16_f32 v69, v70, v71
	v_cvt_pk_bf16_f32 v70, v72, v73
	v_cvt_pk_bf16_f32 v71, v74, v75
	v_cvt_pk_bf16_f32 v72, v76, v77
	v_cvt_pk_bf16_f32 v73, v78, v79
	v_cvt_pk_bf16_f32 v74, v80, v81
	v_cvt_pk_bf16_f32 v75, v82, v83
	v_cvt_pk_bf16_f32 v84, v84, v85
	v_cvt_pk_bf16_f32 v85, v86, v87
	v_cvt_pk_bf16_f32 v86, v88, v89
	v_cvt_pk_bf16_f32 v87, v90, v91
	v_cvt_pk_bf16_f32 v88, v92, v93
	v_cvt_pk_bf16_f32 v89, v94, v95
	v_cvt_pk_bf16_f32 v90, v96, v97
	v_cvt_pk_bf16_f32 v91, v98, v99
	s_waitcnt lgkmcnt(5)
	v_mfma_f32_32x32x16_bf16 v[4:19], v[108:111], v[68:71], v[4:19]
	ds_read_b128 v[108:111], v185 offset:26848
	s_waitcnt lgkmcnt(5)
	v_mfma_f32_32x32x16_bf16 v[20:35], v[112:115], v[68:71], v[20:35]
	ds_read_b128 v[112:115], v185 offset:35552
	s_waitcnt lgkmcnt(5)
	v_mfma_f32_32x32x16_bf16 v[4:19], v[116:119], v[72:75], v[4:19]
	s_waitcnt lgkmcnt(4)
	v_mfma_f32_32x32x16_bf16 v[20:35], v[120:123], v[72:75], v[20:35]
	s_waitcnt lgkmcnt(3)
	v_mfma_f32_32x32x16_bf16 v[4:19], v[100:103], v[84:87], v[4:19]
	s_waitcnt lgkmcnt(2)
	v_mfma_f32_32x32x16_bf16 v[20:35], v[104:107], v[84:87], v[20:35]
	s_waitcnt lgkmcnt(1)
	v_mfma_f32_32x32x16_bf16 v[4:19], v[108:111], v[88:91], v[4:19]
	s_waitcnt lgkmcnt(0)
	v_mfma_f32_32x32x16_bf16 v[20:35], v[112:115], v[88:91], v[20:35]
	s_branch .LBB0_631

.LBB0_906:
	v_ashrrev_i32_e32 v8, 8, v0
	v_ashrrev_i32_e32 v9, 31, v8
	v_lshl_add_u64 v[8:9], v[8:9], 2, s[0:1]
	global_load_dword v7, v[8:9], off
	global_load_dwordx2 v[16:17], v[2:3], off
	v_lshl_add_u64 v[18:19], s[64:65], 0, v[4:5]
	v_lshlrev_b32_sdwa v20, v6, v0 dst_sel:DWORD dst_unused:UNUSED_PAD src0_sel:DWORD src1_sel:BYTE_0
	global_load_dwordx4 v[8:11], v[18:19], off
	global_load_dwordx4 v[12:15], v20, s[58:59]
	v_add_u32_e32 v24, s2, v0
	v_cmp_gt_i32_e32 vcc, s10, v24
	s_and_saveexec_b64 s[12:13], vcc
	s_mov_b64 s[14:15], exec
	v_ashrrev_i32_e32 v28, 8, v24
	v_ashrrev_i32_e32 v29, 31, v28
	v_lshl_add_u64 v[28:29], v[28:29], 2, s[0:1]
	global_load_dword v27, v[28:29], off
	v_lshl_add_u64 v[40:41], v[2:3], 0, s[4:5]
	global_load_dwordx2 v[36:37], v[40:41], off
	v_lshl_add_u64 v[42:43], v[4:5], 0, s[6:7]
	v_lshl_add_u64 v[38:39], s[64:65], 0, v[42:43]
	v_lshlrev_b32_sdwa v44, v6, v24 dst_sel:DWORD dst_unused:UNUSED_PAD src0_sel:DWORD src1_sel:BYTE_0
	global_load_dwordx4 v[28:31], v[38:39], off
	global_load_dwordx4 v[32:35], v44, s[58:59]
	v_lshl_add_u64 v[38:39], s[60:61], 0, v[42:43]
	s_mov_b64 exec, s[12:13]
	v_lshl_add_u64 v[18:19], s[60:61], 0, v[4:5]
	v_add_u32_e32 v0, s2, v24
	v_cmp_lt_i32_e32 vcc, s3, v0
	s_or_b64 s[8:9], vcc, s[8:9]
	v_lshl_add_u64 v[2:3], v[40:41], 0, s[4:5]
	v_lshl_add_u64 v[4:5], v[42:43], 0, s[6:7]
	s_waitcnt vmcnt(0)
	v_fmamk_f32 v7, v7, 0x3a800000, v1
	v_mul_f32_e32 v22, 0x4b800000, v7
	v_cmp_gt_f32_e32 vcc, s10, v7
	v_lshlrev_b32_e32 v20, 16, v16
	v_and_b32_e32 v21, 0xffff0000, v16
	v_cndmask_b32_e32 v7, v7, v22, vcc
	v_rsq_f32_e32 v7, v7
	v_lshlrev_b32_e32 v16, 16, v17
	v_and_b32_e32 v17, 0xffff0000, v17
	v_mul_f32_e32 v22, 0x45800000, v7
	v_cndmask_b32_e32 v22, v7, v22, vcc
	v_pk_mul_f32 v[20:21], v[22:23], v[20:21] op_sel_hi:[0,1]
	v_pk_mul_f32 v[16:17], v[22:23], v[16:17] op_sel_hi:[0,1]
	v_pk_fma_f32 v[8:9], v[12:13], v[20:21], v[8:9]
	v_pk_fma_f32 v[10:11], v[14:15], v[16:17], v[10:11]
	global_store_dwordx4 v[18:19], v[8:11], off
	s_mov_b64 exec, s[14:15]
	v_fmamk_f32 v27, v27, 0x3a800000, v1
	v_mul_f32_e32 v46, 0x4b800000, v27
	v_cmp_gt_f32_e32 vcc, s10, v27
	v_lshlrev_b32_e32 v44, 16, v36
	v_and_b32_e32 v45, 0xffff0000, v36
	v_cndmask_b32_e32 v27, v27, v46, vcc
	v_rsq_f32_e32 v27, v27
	v_lshlrev_b32_e32 v36, 16, v37
	v_and_b32_e32 v37, 0xffff0000, v37
	v_mul_f32_e32 v46, 0x45800000, v27
	v_cndmask_b32_e32 v46, v27, v46, vcc
	v_pk_mul_f32 v[44:45], v[46:47], v[44:45] op_sel_hi:[0,1]
	v_pk_mul_f32 v[36:37], v[46:47], v[36:37] op_sel_hi:[0,1]
	v_pk_fma_f32 v[28:29], v[32:33], v[44:45], v[28:29]
	v_pk_fma_f32 v[30:31], v[34:35], v[36:37], v[30:31]
	global_store_dwordx4 v[38:39], v[28:31], off
	s_mov_b64 exec, s[12:13]
	s_andn2_b64 exec, exec, s[8:9]
	s_cbranch_execnz .LBB0_906
